# selection step B preamble hand-written: only the existing 512-key register blocks are read from LDS and converted (full blocks without per-lane bounds compare), the rest zeroed; reads issued one block
# baseline (speedup 1.0000x reference)
; __device__ __forceinline__ void select_group(unsigned char* ws, int r0, const bf16_t* __restrict__ kib, int n, float* sc, SelPre& pre, int nr0, const bf16_t* __restrict__ nkib, int nn) {
;     ...
;   {
;     const float* rowl = sc + w * 4096 + lane;
;     const int nreg = (n + 63) >> 6;
;     const int nl = n - lane;
;     unsigned x[64];
; #pragma unroll
;     for (int i = 0; i < 64; ++i) {
;       const unsigned ub = __float_as_uint(rowl[i * 64]);
;       const unsigned o = ub ^ ((unsigned)((int)ub >> 31) | 0x80000000u);
;       x[i] = (i * 64 < nl) ? o : 0u;
;     }
.LBB0_2934:
	v_lshlrev_b32_e32 v16, 14, v206
	v_lshlrev_b32_e32 v115, 2, v114
	v_add3_u32 v16, 0, v16, v115
	ds_read_b32 v239, v16 offset:0
	ds_read_b32 v238, v16 offset:256
	ds_read_b32 v237, v16 offset:512
	ds_read_b32 v236, v16 offset:768
	ds_read_b32 v235, v16 offset:1024
	ds_read_b32 v234, v16 offset:1280
	ds_read_b32 v233, v16 offset:1536
	ds_read_b32 v231, v16 offset:1792
	v_sub_u32_e32 v240, s57, v114
	s_add_i32 s38, s57, 63
	s_lshr_b32 s38, s38, 6
	s_add_i32 s38, s38, 7
	s_lshr_b32 s61, s38, 3
	s_mov_b64 s[40:41], 0
	s_cmp_gt_i32 s61, 1
	s_cbranch_scc0 .Lselpre_last0
	ds_read_b32 v232, v16 offset:2048
	ds_read_b32 v230, v16 offset:2304
	ds_read_b32 v229, v16 offset:2560
	ds_read_b32 v228, v16 offset:2816
	ds_read_b32 v227, v16 offset:3072
	ds_read_b32 v226, v16 offset:3328
	ds_read_b32 v225, v16 offset:3584
	ds_read_b32 v223, v16 offset:3840
	s_waitcnt lgkmcnt(12)
	v_ashrrev_i32_e32 v164, 31, v239
	v_bitop3_b32 v239, v164, v239, s58 bitop3:0x36
	v_ashrrev_i32_e32 v164, 31, v238
	v_bitop3_b32 v238, v164, v238, s58 bitop3:0x36
	v_ashrrev_i32_e32 v164, 31, v237
	v_bitop3_b32 v237, v164, v237, s58 bitop3:0x36
	v_ashrrev_i32_e32 v164, 31, v236
	v_bitop3_b32 v236, v164, v236, s58 bitop3:0x36
	s_waitcnt lgkmcnt(8)
	v_ashrrev_i32_e32 v164, 31, v235
	v_bitop3_b32 v235, v164, v235, s58 bitop3:0x36
	v_ashrrev_i32_e32 v164, 31, v234
	v_bitop3_b32 v234, v164, v234, s58 bitop3:0x36
	v_ashrrev_i32_e32 v164, 31, v233
	v_bitop3_b32 v233, v164, v233, s58 bitop3:0x36
	v_ashrrev_i32_e32 v164, 31, v231
	v_bitop3_b32 v231, v164, v231, s58 bitop3:0x36
	s_branch .Lselpre_blk1
.Lselpre_last0:
	s_waitcnt lgkmcnt(4)
	v_ashrrev_i32_e32 v164, 31, v239
	v_bitop3_b32 v239, v164, v239, s58 bitop3:0x36
	v_ashrrev_i32_e32 v164, 31, v238
	v_bitop3_b32 v238, v164, v238, s58 bitop3:0x36
	v_ashrrev_i32_e32 v164, 31, v237
	v_bitop3_b32 v237, v164, v237, s58 bitop3:0x36
	v_ashrrev_i32_e32 v164, 31, v236
	v_bitop3_b32 v236, v164, v236, s58 bitop3:0x36
	s_waitcnt lgkmcnt(0)
	v_ashrrev_i32_e32 v164, 31, v235
	v_cmp_lt_i32_e32 vcc, 0x100, v240
	v_bitop3_b32 v164, v164, v235, s58 bitop3:0x36
	s_nop 0
	v_cndmask_b32_e32 v235, 0, v164, vcc
	v_ashrrev_i32_e32 v164, 31, v234
	v_cmp_lt_i32_e32 vcc, 0x140, v240
	v_bitop3_b32 v164, v164, v234, s58 bitop3:0x36
	s_nop 0
	v_cndmask_b32_e32 v234, 0, v164, vcc
	v_ashrrev_i32_e32 v164, 31, v233
	v_cmp_lt_i32_e32 vcc, 0x180, v240
	v_bitop3_b32 v164, v164, v233, s58 bitop3:0x36
	s_nop 0
	v_cndmask_b32_e32 v233, 0, v164, vcc
	v_ashrrev_i32_e32 v164, 31, v231
	v_cmp_lt_i32_e32 vcc, 0x1c0, v240
	v_bitop3_b32 v164, v164, v231, s58 bitop3:0x36
	s_nop 0
	v_cndmask_b32_e32 v231, 0, v164, vcc
	s_branch .Lselpre_zero1
.Lselpre_blk1:
	s_cmp_gt_i32 s61, 2
	s_cbranch_scc0 .Lselpre_last1
	ds_read_b32 v224, v16 offset:4096
	ds_read_b32 v222, v16 offset:4352
	ds_read_b32 v221, v16 offset:4608
	ds_read_b32 v220, v16 offset:4864
	ds_read_b32 v219, v16 offset:5120
	ds_read_b32 v218, v16 offset:5376
	ds_read_b32 v217, v16 offset:5632
	ds_read_b32 v215, v16 offset:5888
	s_waitcnt lgkmcnt(12)
	v_ashrrev_i32_e32 v164, 31, v232
	v_bitop3_b32 v232, v164, v232, s58 bitop3:0x36
	v_ashrrev_i32_e32 v164, 31, v230
	v_bitop3_b32 v230, v164, v230, s58 bitop3:0x36
	v_ashrrev_i32_e32 v164, 31, v229
	v_bitop3_b32 v229, v164, v229, s58 bitop3:0x36
	v_ashrrev_i32_e32 v164, 31, v228
	v_bitop3_b32 v228, v164, v228, s58 bitop3:0x36
	s_waitcnt lgkmcnt(8)
	v_ashrrev_i32_e32 v164, 31, v227
	v_bitop3_b32 v227, v164, v227, s58 bitop3:0x36
	v_ashrrev_i32_e32 v164, 31, v226
	v_bitop3_b32 v226, v164, v226, s58 bitop3:0x36
	v_ashrrev_i32_e32 v164, 31, v225
	v_bitop3_b32 v225, v164, v225, s58 bitop3:0x36
	v_ashrrev_i32_e32 v164, 31, v223
	v_bitop3_b32 v223, v164, v223, s58 bitop3:0x36
	s_branch .Lselpre_blk2
.Lselpre_last1:
	s_waitcnt lgkmcnt(4)
	v_ashrrev_i32_e32 v164, 31, v232
	v_cmp_lt_i32_e32 vcc, 0x200, v240
	v_bitop3_b32 v164, v164, v232, s58 bitop3:0x36
	s_nop 0
	v_cndmask_b32_e32 v232, 0, v164, vcc
	v_ashrrev_i32_e32 v164, 31, v230
	v_cmp_lt_i32_e32 vcc, 0x240, v240
	v_bitop3_b32 v164, v164, v230, s58 bitop3:0x36
	s_nop 0
	v_cndmask_b32_e32 v230, 0, v164, vcc
	v_ashrrev_i32_e32 v164, 31, v229
	v_cmp_lt_i32_e32 vcc, 0x280, v240
	v_bitop3_b32 v164, v164, v229, s58 bitop3:0x36
	s_nop 0
	v_cndmask_b32_e32 v229, 0, v164, vcc
	v_ashrrev_i32_e32 v164, 31, v228
	v_cmp_lt_i32_e32 vcc, 0x2c0, v240
	v_bitop3_b32 v164, v164, v228, s58 bitop3:0x36
	s_nop 0
	v_cndmask_b32_e32 v228, 0, v164, vcc
	s_waitcnt lgkmcnt(0)
	v_ashrrev_i32_e32 v164, 31, v227
	v_cmp_lt_i32_e32 vcc, 0x300, v240
	v_bitop3_b32 v164, v164, v227, s58 bitop3:0x36
	s_nop 0
	v_cndmask_b32_e32 v227, 0, v164, vcc
	v_ashrrev_i32_e32 v164, 31, v226
	v_cmp_lt_i32_e32 vcc, 0x340, v240
	v_bitop3_b32 v164, v164, v226, s58 bitop3:0x36
	s_nop 0
	v_cndmask_b32_e32 v226, 0, v164, vcc
	v_ashrrev_i32_e32 v164, 31, v225
	v_cmp_lt_i32_e32 vcc, 0x380, v240
	v_bitop3_b32 v164, v164, v225, s58 bitop3:0x36
	s_nop 0
	v_cndmask_b32_e32 v225, 0, v164, vcc
	v_ashrrev_i32_e32 v164, 31, v223
	v_cmp_lt_i32_e32 vcc, 0x3c0, v240
	v_bitop3_b32 v164, v164, v223, s58 bitop3:0x36
	s_nop 0
	v_cndmask_b32_e32 v223, 0, v164, vcc
	s_branch .Lselpre_zero2
; __device__ __forceinline__ void select_group(unsigned char* ws, int r0, const bf16_t* __restrict__ kib, int n, float* sc, SelPre& pre, int nr0, const bf16_t* __restrict__ nkib, int nn) {
;     ...
;   {
;     const float* rowl = sc + w * 4096 + lane;
;     const int nreg = (n + 63) >> 6;
;     const int nl = n - lane;
;     unsigned x[64];
; #pragma unroll
;     for (int i = 0; i < 64; ++i) {
;       const unsigned ub = __float_as_uint(rowl[i * 64]);
;       const unsigned o = ub ^ ((unsigned)((int)ub >> 31) | 0x80000000u);
;       x[i] = (i * 64 < nl) ? o : 0u;
;     }
.Lselpre_blk2:
	s_cmp_gt_i32 s61, 3
	s_cbranch_scc0 .Lselpre_last2
	ds_read_b32 v216, v16 offset:6144
	ds_read_b32 v214, v16 offset:6400
	ds_read_b32 v213, v16 offset:6656
	ds_read_b32 v212, v16 offset:6912
	ds_read_b32 v211, v16 offset:7168
	ds_read_b32 v210, v16 offset:7424
	ds_read_b32 v207, v16 offset:7680
	ds_read_b32 v194, v16 offset:7936
	s_waitcnt lgkmcnt(12)
	v_ashrrev_i32_e32 v164, 31, v224
	v_bitop3_b32 v224, v164, v224, s58 bitop3:0x36
	v_ashrrev_i32_e32 v164, 31, v222
	v_bitop3_b32 v222, v164, v222, s58 bitop3:0x36
	v_ashrrev_i32_e32 v164, 31, v221
	v_bitop3_b32 v221, v164, v221, s58 bitop3:0x36
	v_ashrrev_i32_e32 v164, 31, v220
	v_bitop3_b32 v220, v164, v220, s58 bitop3:0x36
	s_waitcnt lgkmcnt(8)
	v_ashrrev_i32_e32 v164, 31, v219
	v_bitop3_b32 v219, v164, v219, s58 bitop3:0x36
	v_ashrrev_i32_e32 v164, 31, v218
	v_bitop3_b32 v218, v164, v218, s58 bitop3:0x36
	v_ashrrev_i32_e32 v164, 31, v217
	v_bitop3_b32 v217, v164, v217, s58 bitop3:0x36
	v_ashrrev_i32_e32 v164, 31, v215
	v_bitop3_b32 v215, v164, v215, s58 bitop3:0x36
	s_branch .Lselpre_blk3
.Lselpre_last2:
	s_waitcnt lgkmcnt(4)
	v_ashrrev_i32_e32 v164, 31, v224
	v_cmp_lt_i32_e32 vcc, 0x400, v240
	v_bitop3_b32 v164, v164, v224, s58 bitop3:0x36
	s_nop 0
	v_cndmask_b32_e32 v224, 0, v164, vcc
	v_ashrrev_i32_e32 v164, 31, v222
	v_cmp_lt_i32_e32 vcc, 0x440, v240
	v_bitop3_b32 v164, v164, v222, s58 bitop3:0x36
	s_nop 0
	v_cndmask_b32_e32 v222, 0, v164, vcc
	v_ashrrev_i32_e32 v164, 31, v221
	v_cmp_lt_i32_e32 vcc, 0x480, v240
	v_bitop3_b32 v164, v164, v221, s58 bitop3:0x36
	s_nop 0
	v_cndmask_b32_e32 v221, 0, v164, vcc
	v_ashrrev_i32_e32 v164, 31, v220
	v_cmp_lt_i32_e32 vcc, 0x4c0, v240
	v_bitop3_b32 v164, v164, v220, s58 bitop3:0x36
	s_nop 0
	v_cndmask_b32_e32 v220, 0, v164, vcc
	s_waitcnt lgkmcnt(0)
	v_ashrrev_i32_e32 v164, 31, v219
	v_cmp_lt_i32_e32 vcc, 0x500, v240
	v_bitop3_b32 v164, v164, v219, s58 bitop3:0x36
	s_nop 0
	v_cndmask_b32_e32 v219, 0, v164, vcc
	v_ashrrev_i32_e32 v164, 31, v218
	v_cmp_lt_i32_e32 vcc, 0x540, v240
	v_bitop3_b32 v164, v164, v218, s58 bitop3:0x36
	s_nop 0
	v_cndmask_b32_e32 v218, 0, v164, vcc
	v_ashrrev_i32_e32 v164, 31, v217
	v_cmp_lt_i32_e32 vcc, 0x580, v240
	v_bitop3_b32 v164, v164, v217, s58 bitop3:0x36
	s_nop 0
	v_cndmask_b32_e32 v217, 0, v164, vcc
	v_ashrrev_i32_e32 v164, 31, v215
	v_cmp_lt_i32_e32 vcc, 0x5c0, v240
	v_bitop3_b32 v164, v164, v215, s58 bitop3:0x36
	s_nop 0
	v_cndmask_b32_e32 v215, 0, v164, vcc
	s_branch .Lselpre_zero3
.Lselpre_blk3:
	s_cmp_gt_i32 s61, 4
	s_cbranch_scc0 .Lselpre_last3
	ds_read_b32 v195, v16 offset:8192
	ds_read_b32 v193, v16 offset:8448
	ds_read_b32 v192, v16 offset:8704
	ds_read_b32 v191, v16 offset:8960
	ds_read_b32 v190, v16 offset:9216
	ds_read_b32 v189, v16 offset:9472
	ds_read_b32 v188, v16 offset:9728
	ds_read_b32 v186, v16 offset:9984
	s_waitcnt lgkmcnt(12)
	v_ashrrev_i32_e32 v164, 31, v216
	v_bitop3_b32 v216, v164, v216, s58 bitop3:0x36
	v_ashrrev_i32_e32 v164, 31, v214
	v_bitop3_b32 v214, v164, v214, s58 bitop3:0x36
	v_ashrrev_i32_e32 v164, 31, v213
	v_bitop3_b32 v213, v164, v213, s58 bitop3:0x36
	v_ashrrev_i32_e32 v164, 31, v212
	v_bitop3_b32 v212, v164, v212, s58 bitop3:0x36
	s_waitcnt lgkmcnt(8)
	v_ashrrev_i32_e32 v164, 31, v211
	v_bitop3_b32 v211, v164, v211, s58 bitop3:0x36
	v_ashrrev_i32_e32 v164, 31, v210
	v_bitop3_b32 v210, v164, v210, s58 bitop3:0x36
	v_ashrrev_i32_e32 v164, 31, v207
	v_bitop3_b32 v207, v164, v207, s58 bitop3:0x36
	v_ashrrev_i32_e32 v164, 31, v194
	v_bitop3_b32 v194, v164, v194, s58 bitop3:0x36
	s_branch .Lselpre_blk4
.Lselpre_last3:
	s_waitcnt lgkmcnt(4)
	v_ashrrev_i32_e32 v164, 31, v216
	v_cmp_lt_i32_e32 vcc, 0x600, v240
	v_bitop3_b32 v164, v164, v216, s58 bitop3:0x36
	s_nop 0
	v_cndmask_b32_e32 v216, 0, v164, vcc
	v_ashrrev_i32_e32 v164, 31, v214
	v_cmp_lt_i32_e32 vcc, 0x640, v240
	v_bitop3_b32 v164, v164, v214, s58 bitop3:0x36
	s_nop 0
	v_cndmask_b32_e32 v214, 0, v164, vcc
	v_ashrrev_i32_e32 v164, 31, v213
	v_cmp_lt_i32_e32 vcc, 0x680, v240
	v_bitop3_b32 v164, v164, v213, s58 bitop3:0x36
	s_nop 0
	v_cndmask_b32_e32 v213, 0, v164, vcc
	v_ashrrev_i32_e32 v164, 31, v212
	v_cmp_lt_i32_e32 vcc, 0x6c0, v240
	v_bitop3_b32 v164, v164, v212, s58 bitop3:0x36
	s_nop 0
	v_cndmask_b32_e32 v212, 0, v164, vcc
	s_waitcnt lgkmcnt(0)
	v_ashrrev_i32_e32 v164, 31, v211
	v_cmp_lt_i32_e32 vcc, 0x700, v240
	v_bitop3_b32 v164, v164, v211, s58 bitop3:0x36
	s_nop 0
	v_cndmask_b32_e32 v211, 0, v164, vcc
	v_ashrrev_i32_e32 v164, 31, v210
	v_cmp_lt_i32_e32 vcc, 0x740, v240
	v_bitop3_b32 v164, v164, v210, s58 bitop3:0x36
	s_nop 0
	v_cndmask_b32_e32 v210, 0, v164, vcc
	v_ashrrev_i32_e32 v164, 31, v207
	v_cmp_lt_i32_e32 vcc, 0x780, v240
	v_bitop3_b32 v164, v164, v207, s58 bitop3:0x36
	s_nop 0
	v_cndmask_b32_e32 v207, 0, v164, vcc
	v_ashrrev_i32_e32 v164, 31, v194
	v_cmp_lt_i32_e32 vcc, 0x7c0, v240
	v_bitop3_b32 v164, v164, v194, s58 bitop3:0x36
	s_nop 0
	v_cndmask_b32_e32 v194, 0, v164, vcc
	s_branch .Lselpre_zero4
.Lselpre_blk4:
	s_cmp_gt_i32 s61, 5
	s_cbranch_scc0 .Lselpre_last4
	ds_read_b32 v187, v16 offset:10240
	ds_read_b32 v185, v16 offset:10496
	ds_read_b32 v184, v16 offset:10752
	ds_read_b32 v183, v16 offset:11008
	ds_read_b32 v182, v16 offset:11264
	ds_read_b32 v181, v16 offset:11520
	ds_read_b32 v180, v16 offset:11776
	ds_read_b32 v178, v16 offset:12032
	s_waitcnt lgkmcnt(12)
	v_ashrrev_i32_e32 v164, 31, v195
	v_bitop3_b32 v195, v164, v195, s58 bitop3:0x36
	v_ashrrev_i32_e32 v164, 31, v193
	v_bitop3_b32 v193, v164, v193, s58 bitop3:0x36
	v_ashrrev_i32_e32 v164, 31, v192
	v_bitop3_b32 v192, v164, v192, s58 bitop3:0x36
	v_ashrrev_i32_e32 v164, 31, v191
	v_bitop3_b32 v191, v164, v191, s58 bitop3:0x36
	s_waitcnt lgkmcnt(8)
	v_ashrrev_i32_e32 v164, 31, v190
	v_bitop3_b32 v190, v164, v190, s58 bitop3:0x36
	v_ashrrev_i32_e32 v164, 31, v189
	v_bitop3_b32 v189, v164, v189, s58 bitop3:0x36
	v_ashrrev_i32_e32 v164, 31, v188
	v_bitop3_b32 v188, v164, v188, s58 bitop3:0x36
	v_ashrrev_i32_e32 v164, 31, v186
	v_bitop3_b32 v186, v164, v186, s58 bitop3:0x36
	s_branch .Lselpre_blk5
; __device__ __forceinline__ void select_group(unsigned char* ws, int r0, const bf16_t* __restrict__ kib, int n, float* sc, SelPre& pre, int nr0, const bf16_t* __restrict__ nkib, int nn) {
;     ...
;   {
;     const float* rowl = sc + w * 4096 + lane;
;     const int nreg = (n + 63) >> 6;
;     const int nl = n - lane;
;     unsigned x[64];
; #pragma unroll
;     for (int i = 0; i < 64; ++i) {
;       const unsigned ub = __float_as_uint(rowl[i * 64]);
;       const unsigned o = ub ^ ((unsigned)((int)ub >> 31) | 0x80000000u);
;       x[i] = (i * 64 < nl) ? o : 0u;
;     }
.Lselpre_last4:
	s_waitcnt lgkmcnt(4)
	v_ashrrev_i32_e32 v164, 31, v195
	v_cmp_lt_i32_e32 vcc, 0x800, v240
	v_bitop3_b32 v164, v164, v195, s58 bitop3:0x36
	s_nop 0
	v_cndmask_b32_e32 v195, 0, v164, vcc
	v_ashrrev_i32_e32 v164, 31, v193
	v_cmp_lt_i32_e32 vcc, 0x840, v240
	v_bitop3_b32 v164, v164, v193, s58 bitop3:0x36
	s_nop 0
	v_cndmask_b32_e32 v193, 0, v164, vcc
	v_ashrrev_i32_e32 v164, 31, v192
	v_cmp_lt_i32_e32 vcc, 0x880, v240
	v_bitop3_b32 v164, v164, v192, s58 bitop3:0x36
	s_nop 0
	v_cndmask_b32_e32 v192, 0, v164, vcc
	v_ashrrev_i32_e32 v164, 31, v191
	v_cmp_lt_i32_e32 vcc, 0x8c0, v240
	v_bitop3_b32 v164, v164, v191, s58 bitop3:0x36
	s_nop 0
	v_cndmask_b32_e32 v191, 0, v164, vcc
	s_waitcnt lgkmcnt(0)
	v_ashrrev_i32_e32 v164, 31, v190
	v_cmp_lt_i32_e32 vcc, 0x900, v240
	v_bitop3_b32 v164, v164, v190, s58 bitop3:0x36
	s_nop 0
	v_cndmask_b32_e32 v190, 0, v164, vcc
	v_ashrrev_i32_e32 v164, 31, v189
	v_cmp_lt_i32_e32 vcc, 0x940, v240
	v_bitop3_b32 v164, v164, v189, s58 bitop3:0x36
	s_nop 0
	v_cndmask_b32_e32 v189, 0, v164, vcc
	v_ashrrev_i32_e32 v164, 31, v188
	v_cmp_lt_i32_e32 vcc, 0x980, v240
	v_bitop3_b32 v164, v164, v188, s58 bitop3:0x36
	s_nop 0
	v_cndmask_b32_e32 v188, 0, v164, vcc
	v_ashrrev_i32_e32 v164, 31, v186
	v_cmp_lt_i32_e32 vcc, 0x9c0, v240
	v_bitop3_b32 v164, v164, v186, s58 bitop3:0x36
	s_nop 0
	v_cndmask_b32_e32 v186, 0, v164, vcc
	s_branch .Lselpre_zero5
.Lselpre_blk5:
	s_cmp_gt_i32 s61, 6
	s_cbranch_scc0 .Lselpre_last5
	ds_read_b32 v179, v16 offset:12288
	ds_read_b32 v177, v16 offset:12544
	ds_read_b32 v176, v16 offset:12800
	ds_read_b32 v175, v16 offset:13056
	ds_read_b32 v174, v16 offset:13312
	ds_read_b32 v173, v16 offset:13568
	ds_read_b32 v172, v16 offset:13824
	ds_read_b32 v115, v16 offset:14080
	s_waitcnt lgkmcnt(12)
	v_ashrrev_i32_e32 v164, 31, v187
	v_bitop3_b32 v187, v164, v187, s58 bitop3:0x36
	v_ashrrev_i32_e32 v164, 31, v185
	v_bitop3_b32 v185, v164, v185, s58 bitop3:0x36
	v_ashrrev_i32_e32 v164, 31, v184
	v_bitop3_b32 v184, v164, v184, s58 bitop3:0x36
	v_ashrrev_i32_e32 v164, 31, v183
	v_bitop3_b32 v183, v164, v183, s58 bitop3:0x36
	s_waitcnt lgkmcnt(8)
	v_ashrrev_i32_e32 v164, 31, v182
	v_bitop3_b32 v182, v164, v182, s58 bitop3:0x36
	v_ashrrev_i32_e32 v164, 31, v181
	v_bitop3_b32 v181, v164, v181, s58 bitop3:0x36
	v_ashrrev_i32_e32 v164, 31, v180
	v_bitop3_b32 v180, v164, v180, s58 bitop3:0x36
	v_ashrrev_i32_e32 v164, 31, v178
	v_bitop3_b32 v178, v164, v178, s58 bitop3:0x36
	s_branch .Lselpre_blk6
.Lselpre_last5:
	s_waitcnt lgkmcnt(4)
	v_ashrrev_i32_e32 v164, 31, v187
	v_cmp_lt_i32_e32 vcc, 0xa00, v240
	v_bitop3_b32 v164, v164, v187, s58 bitop3:0x36
	s_nop 0
	v_cndmask_b32_e32 v187, 0, v164, vcc
	v_ashrrev_i32_e32 v164, 31, v185
	v_cmp_lt_i32_e32 vcc, 0xa40, v240
	v_bitop3_b32 v164, v164, v185, s58 bitop3:0x36
	s_nop 0
	v_cndmask_b32_e32 v185, 0, v164, vcc
	v_ashrrev_i32_e32 v164, 31, v184
	v_cmp_lt_i32_e32 vcc, 0xa80, v240
	v_bitop3_b32 v164, v164, v184, s58 bitop3:0x36
	s_nop 0
	v_cndmask_b32_e32 v184, 0, v164, vcc
	v_ashrrev_i32_e32 v164, 31, v183
	v_cmp_lt_i32_e32 vcc, 0xac0, v240
	v_bitop3_b32 v164, v164, v183, s58 bitop3:0x36
	s_nop 0
	v_cndmask_b32_e32 v183, 0, v164, vcc
	s_waitcnt lgkmcnt(0)
	v_ashrrev_i32_e32 v164, 31, v182
	v_cmp_lt_i32_e32 vcc, 0xb00, v240
	v_bitop3_b32 v164, v164, v182, s58 bitop3:0x36
	s_nop 0
	v_cndmask_b32_e32 v182, 0, v164, vcc
	v_ashrrev_i32_e32 v164, 31, v181
	v_cmp_lt_i32_e32 vcc, 0xb40, v240
	v_bitop3_b32 v164, v164, v181, s58 bitop3:0x36
	s_nop 0
	v_cndmask_b32_e32 v181, 0, v164, vcc
	v_ashrrev_i32_e32 v164, 31, v180
	v_cmp_lt_i32_e32 vcc, 0xb80, v240
	v_bitop3_b32 v164, v164, v180, s58 bitop3:0x36
	s_nop 0
	v_cndmask_b32_e32 v180, 0, v164, vcc
	v_ashrrev_i32_e32 v164, 31, v178
	v_cmp_lt_i32_e32 vcc, 0xbc0, v240
	v_bitop3_b32 v164, v164, v178, s58 bitop3:0x36
	s_nop 0
	v_cndmask_b32_e32 v178, 0, v164, vcc
	s_branch .Lselpre_zero6
; __device__ __forceinline__ void select_group(unsigned char* ws, int r0, const bf16_t* __restrict__ kib, int n, float* sc, SelPre& pre, int nr0, const bf16_t* __restrict__ nkib, int nn) {
;     ...
;   {
;     const float* rowl = sc + w * 4096 + lane;
;     const int nreg = (n + 63) >> 6;
;     const int nl = n - lane;
;     unsigned x[64];
; #pragma unroll
;     for (int i = 0; i < 64; ++i) {
;       const unsigned ub = __float_as_uint(rowl[i * 64]);
;       const unsigned o = ub ^ ((unsigned)((int)ub >> 31) | 0x80000000u);
;       x[i] = (i * 64 < nl) ? o : 0u;
;     }
;     unsigned tau = 0u;
;     int cge = 0;
;     switch ((nreg + 7) >> 3) {
;       case 1: bisect256<1>(x, tau, cge); break;
;       case 2: bisect256<2>(x, tau, cge); break;
;       case 3: bisect256<3>(x, tau, cge); break;
;       case 4: bisect256<4>(x, tau, cge); break;
;       case 5: bisect256<5>(x, tau, cge); break;
;       case 6: bisect256<6>(x, tau, cge); break;
;       case 7: bisect256<7>(x, tau, cge); break;
;       default: bisect256<8>(x, tau, cge); break;
;     }
.Lselpre_blk6:
	s_waitcnt lgkmcnt(4)
	v_ashrrev_i32_e32 v164, 31, v179
	v_cmp_lt_i32_e32 vcc, 0xc00, v240
	v_bitop3_b32 v164, v164, v179, s58 bitop3:0x36
	s_nop 0
	v_cndmask_b32_e32 v179, 0, v164, vcc
	v_ashrrev_i32_e32 v164, 31, v177
	v_cmp_lt_i32_e32 vcc, 0xc40, v240
	v_bitop3_b32 v164, v164, v177, s58 bitop3:0x36
	s_nop 0
	v_cndmask_b32_e32 v177, 0, v164, vcc
	v_ashrrev_i32_e32 v164, 31, v176
	v_cmp_lt_i32_e32 vcc, 0xc80, v240
	v_bitop3_b32 v164, v164, v176, s58 bitop3:0x36
	s_nop 0
	v_cndmask_b32_e32 v176, 0, v164, vcc
	v_ashrrev_i32_e32 v164, 31, v175
	v_cmp_lt_i32_e32 vcc, 0xcc0, v240
	v_bitop3_b32 v164, v164, v175, s58 bitop3:0x36
	s_nop 0
	v_cndmask_b32_e32 v175, 0, v164, vcc
	s_waitcnt lgkmcnt(0)
	v_ashrrev_i32_e32 v164, 31, v174
	v_cmp_lt_i32_e32 vcc, 0xd00, v240
	v_bitop3_b32 v164, v164, v174, s58 bitop3:0x36
	s_nop 0
	v_cndmask_b32_e32 v174, 0, v164, vcc
	v_ashrrev_i32_e32 v164, 31, v173
	v_cmp_lt_i32_e32 vcc, 0xd40, v240
	v_bitop3_b32 v164, v164, v173, s58 bitop3:0x36
	s_nop 0
	v_cndmask_b32_e32 v173, 0, v164, vcc
	v_ashrrev_i32_e32 v164, 31, v172
	v_cmp_lt_i32_e32 vcc, 0xd80, v240
	v_bitop3_b32 v164, v164, v172, s58 bitop3:0x36
	s_nop 0
	v_cndmask_b32_e32 v172, 0, v164, vcc
	v_ashrrev_i32_e32 v164, 31, v115
	v_cmp_lt_i32_e32 vcc, 0xdc0, v240
	v_bitop3_b32 v164, v164, v115, s58 bitop3:0x36
	s_nop 0
	v_cndmask_b32_e32 v115, 0, v164, vcc
	s_branch .Lselpre_tail
.Lselpre_zero1:
	v_mov_b32_e32 v232, 0
	v_mov_b32_e32 v230, 0
	v_mov_b32_e32 v229, 0
	v_mov_b32_e32 v228, 0
	v_mov_b32_e32 v227, 0
	v_mov_b32_e32 v226, 0
	v_mov_b32_e32 v225, 0
	v_mov_b32_e32 v223, 0
.Lselpre_zero2:
	v_mov_b32_e32 v224, 0
	v_mov_b32_e32 v222, 0
	v_mov_b32_e32 v221, 0
	v_mov_b32_e32 v220, 0
	v_mov_b32_e32 v219, 0
	v_mov_b32_e32 v218, 0
	v_mov_b32_e32 v217, 0
	v_mov_b32_e32 v215, 0
.Lselpre_zero3:
	v_mov_b32_e32 v216, 0
	v_mov_b32_e32 v214, 0
	v_mov_b32_e32 v213, 0
	v_mov_b32_e32 v212, 0
	v_mov_b32_e32 v211, 0
	v_mov_b32_e32 v210, 0
	v_mov_b32_e32 v207, 0
	v_mov_b32_e32 v194, 0
.Lselpre_zero4:
	v_mov_b32_e32 v195, 0
	v_mov_b32_e32 v193, 0
	v_mov_b32_e32 v192, 0
	v_mov_b32_e32 v191, 0
	v_mov_b32_e32 v190, 0
	v_mov_b32_e32 v189, 0
	v_mov_b32_e32 v188, 0
	v_mov_b32_e32 v186, 0
.Lselpre_zero5:
	v_mov_b32_e32 v187, 0
	v_mov_b32_e32 v185, 0
	v_mov_b32_e32 v184, 0
	v_mov_b32_e32 v183, 0
	v_mov_b32_e32 v182, 0
	v_mov_b32_e32 v181, 0
	v_mov_b32_e32 v180, 0
	v_mov_b32_e32 v178, 0
.Lselpre_zero6:
	v_mov_b32_e32 v179, 0
	v_mov_b32_e32 v177, 0
	v_mov_b32_e32 v176, 0
	v_mov_b32_e32 v175, 0
	v_mov_b32_e32 v174, 0
	v_mov_b32_e32 v173, 0
	v_mov_b32_e32 v172, 0
	v_mov_b32_e32 v115, 0
.Lselpre_tail:
	ds_read2st64_b32 v[170:171], v16 offset0:56 offset1:57
	ds_read2st64_b32 v[168:169], v16 offset0:58 offset1:59
	ds_read2st64_b32 v[166:167], v16 offset0:60 offset1:61
	ds_read2st64_b32 v[164:165], v16 offset0:62 offset1:63
	s_movk_i32 s0, 0xe00
	v_cmp_lt_i32_e64 s[12:13], s0, v240
	s_movk_i32 s0, 0xe40
	v_cmp_lt_i32_e64 s[6:7], s0, v240
	s_movk_i32 s0, 0xe80
	v_cmp_lt_i32_e64 s[8:9], s0, v240
	s_movk_i32 s0, 0xec0
	v_cmp_lt_i32_e64 s[2:3], s0, v240
	s_movk_i32 s0, 0xf00
	v_cmp_lt_i32_e64 s[4:5], s0, v240
	s_movk_i32 s10, 0xf80
	v_cmp_lt_i32_e64 s[14:15], s10, v240
	s_movk_i32 s10, 0xfc0
	v_cmp_lt_i32_e64 s[10:11], s10, v240
	s_movk_i32 s0, 0xf40
	v_cmp_lt_i32_e64 s[0:1], s0, v240
	s_cmp_lt_i32 s61, 4
	s_cbranch_scc1 .LBB0_2941
	s_cmp_gt_i32 s61, 5
	s_cbranch_scc0 .LBB0_2942
	s_cmp_gt_i32 s61, 6
	s_cbranch_scc0 .LBB0_2943
	s_cmp_eq_u32 s61, 7
	s_cbranch_scc0 .LBB0_2944
	s_mov_b32 s59, 0
	v_mov_b32_e32 v240, 31
	v_mov_b32_e32 v16, 0
